# P2 A/B item sets of workgroups 63<->128 and 127<->129 swapped: the sequence-final items (extra state stores) no longer fall on workgroups that also own a chunk item
# baseline (speedup 1.0000x reference)
.LBB0_428:
	s_or_b64 exec, exec, s[2:3]
	s_abs_i32 s0, s46
	v_cvt_f32_u32_e32 v1, s0
	s_sub_i32 s1, 0, s0
	s_movk_i32 s3, 0x352
	s_mov_b32 s15, 0
	v_rcp_iflag_f32_e32 v1, v1
	s_mov_b32 s66, 0x2100000
	s_mov_b32 s64, s58
	v_mov_b32_e32 v155, 0
	v_mul_f32_e32 v1, 0x4f7ffffe, v1
	v_cvt_u32_f32_e32 v1, v1
	v_mov_b32_e32 v180, 1
	v_mov_b64_e32 v[156:157], 0x39c
	v_mov_b64_e32 v[158:159], 0x39b
	v_readfirstlane_b32 s2, v1
	s_mul_i32 s1, s1, s2
	s_mul_hi_u32 s1, s2, s1
	s_add_i32 s2, s2, s1
	s_mul_hi_u32 s1, s2, 0x39c
	s_mul_i32 s1, s1, s0
	s_sub_i32 s1, 0x39c, s1
	s_sub_i32 s7, s1, s0
	s_cmp_ge_u32 s1, s0
	s_cselect_b32 s1, s7, s1
	s_sub_i32 s7, s1, s0
	s_cmp_ge_u32 s1, s0
	s_cselect_b32 s1, s7, s1
	s_sub_i32 s20, s46, s1
	s_sub_i32 s7, s24, s1
	s_cmp_gt_i32 s7, -1
	s_cselect_b64 s[8:9], -1, 0
	v_writelane_b32 v244, s8, 12
	s_cmp_lg_u32 s1, 0
	v_mbcnt_hi_u32_b32 v181, -1, v40
	v_writelane_b32 v244, s9, 13
	s_cselect_b64 s[8:9], -1, 0
	s_bitcmp0_b32 s7, 0
	v_writelane_b32 v244, s8, 14
	s_cselect_b32 s14, s3, 0x6a4
	s_cmpk_lt_u32 s7, 0x1c0
	v_writelane_b32 v244, s9, 15
	s_cselect_b64 s[8:9], -1, 0
	v_writelane_b32 v244, s8, 16
	v_mov_b64_e32 v[160:161], 0xff
	v_mov_b64_e32 v[162:163], 0x100
	v_writelane_b32 v244, s9, 17
	s_add_u32 s8, s74, 0xd80000
	s_addc_u32 s9, s75, 0
	v_writelane_b32 v244, s8, 18
	s_mov_b32 s75, 0x20000
	s_mov_b32 s74, 0x4200000
	v_writelane_b32 v244, s9, 19
	s_add_u32 s8, s72, 0x1000
	s_addc_u32 s9, s73, 0
	v_writelane_b32 v244, s8, 20
	s_add_u32 s3, s52, 0x700000
	s_mov_b32 s67, s75
	v_writelane_b32 v244, s9, 21
	v_writelane_b32 v244, s3, 22
	s_addc_u32 s3, s53, 0
	s_cmp_lg_u64 s[72:73], 0
	v_writelane_b32 v244, s3, 23
	s_cselect_b64 s[8:9], -1, 0
	v_writelane_b32 v244, s8, 24
	s_cmpk_lt_i32 s7, 0x80
	s_mov_b32 s72, s60
	v_writelane_b32 v244, s9, 25
	s_cselect_b64 s[8:9], -1, 0
	s_add_u32 s26, s94, 0x400000
	s_addc_u32 s27, s95, 0
	s_add_u32 s21, s54, 0x200000
	v_writelane_b32 v244, s7, 26
	s_addc_u32 s28, s55, 0
	v_writelane_b32 v244, s8, 27
	s_cmpk_lt_i32 s24, 0x39c
	s_movk_i32 s25, 0x204
	v_writelane_b32 v244, s9, 28
	s_cselect_b64 s[8:9], -1, 0
	v_writelane_b32 v244, s8, 29
	s_ashr_i32 s3, s24, 31
	s_ashr_i32 s47, s46, 31
	v_writelane_b32 v244, s9, 30
	v_writelane_b32 v244, s3, 31
	s_lshr_b32 s3, s3, 29
	s_add_i32 s3, s24, s3
	s_ashr_i32 s8, s3, 3
	s_and_b32 s3, s3, -8
	s_sub_i32 s10, s24, s3
	s_mul_i32 s3, s10, 0x73
	s_add_i32 s11, s3, 4
	s_and_b32 s73, s61, 0xffff
	s_add_u32 s12, s96, 0x200
	s_addc_u32 s13, s97, 0
	v_writelane_b32 v244, s12, 32
	s_mov_b32 s33, 0x800000
	s_mov_b64 s[44:45], 0x80
	v_writelane_b32 v244, s13, 33
	s_add_u32 s12, s96, 0x1000
	s_addc_u32 s13, s97, 0
	v_writelane_b32 v244, s12, 34
	s_waitcnt lgkmcnt(0)
	s_barrier
	v_writelane_b32 v244, s13, 35
	s_add_u32 s12, s96, 0x1100
	s_addc_u32 s13, s97, 0
	v_writelane_b32 v244, s12, 36
	s_nop 1
	v_writelane_b32 v244, s13, 37
	s_add_u32 s12, s96, 0x1200
	s_addc_u32 s13, s97, 0
	v_writelane_b32 v244, s12, 38
	s_nop 1
	v_writelane_b32 v244, s13, 39
	s_add_u32 s12, s96, 0x1300
	s_addc_u32 s13, s97, 0
	v_writelane_b32 v244, s12, 40
	s_cmp_eq_u32 s4, 15
	s_nop 0
	v_writelane_b32 v244, s13, 41
	s_cselect_b64 s[12:13], -1, 0
	v_writelane_b32 v244, s12, 42
	s_cmp_eq_u32 s4, 14
	s_nop 0
	v_writelane_b32 v244, s13, 43
	s_cselect_b64 s[12:13], -1, 0
	v_writelane_b32 v244, s12, 44
	s_cmp_eq_u32 s4, 13
	s_nop 0
	v_writelane_b32 v244, s13, 45
	s_cselect_b64 s[12:13], -1, 0
	v_writelane_b32 v244, s12, 46
	s_cmp_eq_u32 s4, 12
	s_nop 0
	v_writelane_b32 v244, s13, 47
	s_cselect_b64 s[12:13], -1, 0
	v_writelane_b32 v244, s12, 48
	s_cmp_eq_u32 s4, 11
	s_nop 0
	v_writelane_b32 v244, s13, 49
	s_cselect_b64 s[12:13], -1, 0
	v_writelane_b32 v244, s12, 50
	s_cmp_eq_u32 s4, 10
	s_nop 0
	v_writelane_b32 v244, s13, 51
	s_cselect_b64 s[12:13], -1, 0
	v_writelane_b32 v244, s12, 52
	s_cmp_eq_u32 s4, 9
	s_nop 0
	v_writelane_b32 v244, s13, 53
	s_cselect_b64 s[12:13], -1, 0
	v_writelane_b32 v244, s12, 54
	s_cmp_eq_u32 s4, 8
	s_nop 0
	v_writelane_b32 v244, s13, 55
	s_cselect_b64 s[12:13], -1, 0
	v_writelane_b32 v244, s12, 56
	s_cmp_eq_u32 s4, 7
	s_nop 0
	v_writelane_b32 v244, s13, 57
	s_cselect_b64 s[12:13], -1, 0
	v_writelane_b32 v244, s12, 58
	s_cmp_eq_u32 s4, 6
	s_nop 0
	v_writelane_b32 v244, s13, 59
	s_cselect_b64 s[12:13], -1, 0
	v_writelane_b32 v244, s12, 60
	s_cmp_eq_u32 s4, 5
	s_nop 0
	v_writelane_b32 v244, s13, 61
	s_cselect_b64 s[12:13], -1, 0
	v_writelane_b32 v244, s12, 62
	s_cmp_eq_u32 s4, 4
	s_nop 0
	v_writelane_b32 v244, s13, 63
	s_cselect_b64 s[12:13], -1, 0
	v_writelane_b32 v243, s12, 0
	s_cmp_eq_u32 s4, 3
	s_nop 0
	v_writelane_b32 v243, s13, 1
	s_cselect_b64 s[12:13], -1, 0
	v_writelane_b32 v243, s12, 2
	s_cmp_eq_u32 s4, 2
	s_nop 0
	v_writelane_b32 v243, s13, 3
	s_cselect_b64 s[12:13], -1, 0
	v_writelane_b32 v243, s12, 4
	s_cmp_eq_u32 s4, 1
	s_nop 0
	v_writelane_b32 v243, s13, 5
	s_cselect_b64 s[12:13], -1, 0
	v_writelane_b32 v243, s12, 6
	s_cmp_eq_u32 s4, 0
	s_nop 0
	v_writelane_b32 v243, s13, 7
	s_cselect_b64 s[12:13], -1, 0
	s_lshl_b32 s3, s4, 8
	s_add_u32 s3, s96, s3
	v_writelane_b32 v243, s12, 8
	s_addc_u32 s4, s97, 0
	s_nop 0
	v_writelane_b32 v243, s13, 9
	s_add_u32 s12, s3, 0x1400
	s_addc_u32 s13, s4, 0
	v_writelane_b32 v243, s12, 10
	s_nop 1
	v_writelane_b32 v243, s13, 11
	s_add_u32 s12, s3, 0x2400
	s_addc_u32 s13, s4, 0
	v_writelane_b32 v243, s12, 12
	s_nop 1
	v_writelane_b32 v243, s13, 13
	s_add_u32 s12, s96, 0x3400
	s_addc_u32 s13, s97, 0
	v_writelane_b32 v243, s12, 14
	s_nop 1
	v_writelane_b32 v243, s13, 15
	s_add_u32 s12, s96, 0x3500
	s_addc_u32 s13, s97, 0
	v_writelane_b32 v243, s12, 16
	s_cmp_eq_u32 s6, 0
	s_nop 0
	v_writelane_b32 v243, s13, 17
	s_cselect_b64 s[12:13], -1, 0
	s_cmp_lg_u32 s6, 0
	v_writelane_b32 v243, s12, 18
	s_cselect_b64 s[6:7], -1, 0
	s_cmpk_lt_i32 s24, 0x200
	v_writelane_b32 v243, s13, 19
	s_cselect_b64 s[12:13], -1, 0
	v_writelane_b32 v243, s12, 20
	s_and_b64 s[6:7], s[12:13], s[6:7]
	s_mov_b32 s3, s24
	s_cmp_eq_u32 s24, 63
	s_cselect_b32 s3, 0x80, s3
	s_cmp_eq_u32 s24, 0x80
	s_cselect_b32 s3, 63, s3
	s_cmp_eq_u32 s24, 0x7f
	s_cselect_b32 s3, 0x81, s3
	s_cmp_eq_u32 s24, 0x81
	s_cselect_b32 s3, 0x7f, s3
	s_nop 0
	v_writelane_b32 v242, s3, 63
	s_lshl_b32 s3, s3, 5
	v_writelane_b32 v243, s13, 21
	v_writelane_b32 v243, s6, 22
	s_orn2_b32 s4, 0xfffff81f, s3
	s_nop 0
	v_writelane_b32 v243, s7, 23
	v_writelane_b32 v243, s4, 24
	v_writelane_b32 v243, s3, 25
	s_orn2_b32 s3, 0xfffff83f, s3
	s_cmpk_lt_i32 s24, 0x80
	v_writelane_b32 v243, s3, 26
	s_cselect_b64 s[6:7], -1, 0
	v_writelane_b32 v243, s6, 27
	s_add_i32 s3, s46, s24
	s_add_u32 s4, s50, 0x42c0000
	v_writelane_b32 v243, s7, 28
	v_writelane_b32 v243, s4, 29
	s_addc_u32 s4, s51, 0
	s_and_b32 s9, s63, 0xffff
	s_add_u32 s6, s50, 0x4200000
	v_writelane_b32 v243, s4, 30
	s_addc_u32 s7, s51, 0
	v_writelane_b32 v243, s6, 31
	s_add_u32 s4, s50, 0x42b4000
	s_nop 0
	v_writelane_b32 v243, s7, 32
	v_writelane_b32 v243, s4, 33
	s_addc_u32 s4, s51, 0
	v_writelane_b32 v243, s4, 34
	s_add_u32 s4, s50, 0x42b4600
	v_writelane_b32 v243, s4, 35
	s_addc_u32 s4, s51, 0
	s_cmpk_lt_i32 s24, 0x100
	v_writelane_b32 v243, s4, 36
	s_cselect_b64 s[6:7], -1, 0
	v_writelane_b32 v243, s6, 37
	s_lshl_b32 s4, s10, 5
	s_and_b32 s65, s59, 0xffff
	v_writelane_b32 v243, s7, 38
	s_cmp_lt_i32 s10, 4
	s_mul_i32 s6, s10, 0x74
	s_cselect_b32 s6, s6, s11
	s_add_i32 s6, s6, s8
	s_mul_hi_i32 s7, s6, 0x92492493
	s_add_i32 s7, s7, s6
	s_lshr_b32 s11, s7, 31
	s_ashr_i32 s7, s7, 6
	s_add_i32 s7, s7, s11
	s_mul_i32 s11, s7, 0x70
	s_lshl_b32 s12, s7, 3
	s_sub_i32 s11, s6, s11
	s_sub_i32 s6, 0x42, s12
	s_min_u32 s13, s6, 8
	s_cmp_lt_i32 s10, 0
	s_mul_i32 s10, s10, 33
	s_cselect_b32 s4, s10, s4
	s_add_i32 s4, s4, s8
	s_ashr_i32 s6, s4, 31
	s_lshr_b32 s6, s6, 27
	s_add_i32 s6, s4, s6
	s_and_b32 s7, s6, 0xffe0
	s_sub_i32 s4, s4, s7
	s_bfe_i32 s7, s4, 0x80000
	s_bfe_u32 s7, s7, 0x3000c
	s_add_i32 s7, s4, s7
	s_and_b32 s8, s7, 0xf8
	s_sub_i32 s4, s4, s8
	s_ashr_i32 s6, s6, 5
	s_bfe_i32 s7, s7, 0x80000
	s_lshl_b32 s6, s6, 3
	s_sext_i32_i16 s7, s7
	s_sext_i32_i8 s4, s4
	s_add_i32 s16, s6, s4
	s_ashr_i32 s4, s7, 3
	v_writelane_b32 v243, s4, 39
	s_lshr_b32 s4, s7, 3
	v_cvt_f32_ubyte0_e32 v2, s13
	s_bfe_i64 s[6:7], s[4:5], 0x100000
	v_cvt_f32_i32_e32 v1, s11
	v_rcp_iflag_f32_e32 v3, v2
	s_lshl_b64 s[6:7], s[6:7], 19
	s_ashr_i32 s17, s16, 31
	v_writelane_b32 v243, s6, 40
	s_mov_b32 s4, s16
	v_mul_f32_e32 v3, v1, v3
	v_writelane_b32 v243, s7, 41
	s_lshl_b64 s[6:7], s[16:17], 19
	v_writelane_b32 v243, s4, 42
	s_add_u32 s6, s62, s6
	s_addc_u32 s7, s63, s7
	v_writelane_b32 v243, s5, 43
	v_trunc_f32_e32 v3, v3
	s_add_u32 s16, s6, 0x40000
	v_writelane_b32 v243, s6, 44
	v_fma_f32 v1, -v3, v2, v1
	s_addc_u32 s17, s7, 0
	v_writelane_b32 v243, s7, 45
	v_cmp_ge_f32_e64 s[6:7], |v1|, v2
	v_cvt_i32_f32_e32 v1, v3
	s_ashr_i32 s4, s11, 30
	s_or_b32 s4, s4, 1
	s_and_b64 s[6:7], s[6:7], exec
	s_cselect_b32 s4, s4, 0
	v_readfirstlane_b32 s6, v1
	s_add_i32 s4, s6, s4
	s_mul_i32 s6, s4, s13
	s_sub_i32 s6, s11, s6
	v_writelane_b32 v243, s16, 46
	s_sext_i32_i8 s6, s6
	s_add_i32 s6, s12, s6
	v_writelane_b32 v243, s17, 47
	v_writelane_b32 v243, s6, 48
	s_lshr_b32 s6, s2, 25
	s_mul_i32 s6, s6, s0
	s_sub_i32 s6, 0x80, s6
	s_sub_i32 s7, s6, s0
	s_cmp_ge_u32 s6, s0
	s_cselect_b32 s6, s7, s6
	s_sub_i32 s7, s6, s0
	s_cmp_ge_u32 s6, s0
	s_cselect_b32 s6, s7, s6
	s_sub_i32 s3, s3, s6
	s_abs_i32 s6, s3
	s_mul_hi_u32 s2, s6, s2
	s_mul_i32 s2, s2, s0
	s_sub_i32 s2, s6, s2
	s_ashr_i32 s3, s3, 31
	s_sub_i32 s6, s2, s0
	s_cmp_ge_u32 s2, s0
	s_cselect_b32 s2, s6, s2
	s_sub_i32 s6, s2, s0
	s_cmp_ge_u32 s2, s0
	s_cselect_b32 s0, s6, s2
	s_xor_b32 s0, s0, s3
	s_sub_i32 s6, s0, s3
	s_cmpk_lt_i32 s6, 0x80
	s_cselect_b64 s[2:3], -1, 0
	v_writelane_b32 v243, s2, 49
	s_lshl_b32 s0, s1, 3
	s_lshl_b32 s18, s46, 7
	v_writelane_b32 v243, s3, 50
	s_sub_i32 s2, s5, s0
	v_writelane_b32 v243, s2, 51
	s_lshl_b32 s2, s46, 3
	s_sub_i32 s29, s2, s0
	s_lshl_b32 s0, s1, 7
	s_lshl_b32 s1, s24, 7
	v_writelane_b32 v243, s1, 52
	s_sub_i32 s1, s1, s0
	s_sub_i32 s19, s18, s0
	v_writelane_b32 v243, s1, 53
	s_add_u32 s0, s76, 8
	v_writelane_b32 v243, s0, 54
	s_addc_u32 s0, s77, 0
	s_ashr_i32 s7, s6, 31
	v_writelane_b32 v243, s0, 55
	s_lshl_b64 s[0:1], s[6:7], 14
	s_add_u32 s0, s60, s0
	s_addc_u32 s1, s61, s1
	s_add_u32 s0, s0, 0x4003e00
	s_addc_u32 s1, s1, 0
	v_writelane_b32 v243, s0, 56
	s_mov_b32 s8, s62
	v_mov_b32_e32 v1, 0x358637bd
	v_writelane_b32 v243, s1, 57
	s_lshl_b64 s[0:1], s[46:47], 14
	v_writelane_b32 v243, s0, 58
	s_nop 1
	v_writelane_b32 v243, s1, 59
	s_mov_b32 s0, s6
	v_writelane_b32 v243, s0, 60
	s_nop 1
	v_writelane_b32 v243, s1, 61
	s_lshl_b64 s[0:1], s[6:7], 13
	s_add_u32 s0, s62, s0
	s_addc_u32 s1, s63, s1
	s_add_u32 s0, s0, 0x2000000
	s_addc_u32 s1, s1, 0
	v_writelane_b32 v243, s0, 62
	s_nop 1
	v_writelane_b32 v243, s1, 63
	s_mov_b32 s1, 0
	v_writelane_b32 v242, s0, 0
	s_nop 1
	v_writelane_b32 v242, s1, 1
	v_writelane_b32 v242, s14, 2
	s_sext_i32_i8 s0, s4
	s_nop 0
	v_writelane_b32 v242, s15, 3
	v_writelane_b32 v242, s0, 4
	s_lshl_b32 s0, s24, 6
	v_writelane_b32 v242, s0, 5
	s_lshl_b32 s0, s46, 6
	v_writelane_b32 v242, s0, 6
	s_lshl_b32 s0, s24, 1
	v_writelane_b32 v242, s0, 7
	s_lshl_b32 s0, s46, 1
	v_writelane_b32 v242, s0, 8
	s_add_i32 s0, 32, 0x16020
	v_writelane_b32 v242, s0, 9
	s_add_i32 s0, 32, 0x16060
	v_writelane_b32 v242, s0, 10
	s_add_i32 s0, 32, 0x160a0
	v_writelane_b32 v242, s0, 11
	s_add_i32 s0, 32, 0x160e0
	v_writelane_b32 v242, s0, 12
	s_add_i32 s0, 32, 0x16120
	v_writelane_b32 v242, s0, 13
	s_add_i32 s0, 32, 0x16160
	v_writelane_b32 v242, s0, 14
	s_add_i32 s0, 32, 0x161a0
	v_writelane_b32 v242, s0, 15
	s_add_i32 s0, 32, 0x161e0
	v_writelane_b32 v242, s0, 16
	s_add_i32 s0, 32, 0x16030
	v_writelane_b32 v242, s0, 17
	s_add_i32 s0, 32, 0x16070
	v_writelane_b32 v242, s0, 18
	s_add_i32 s0, 32, 0x160b0
	v_writelane_b32 v242, s0, 19
	s_add_i32 s0, 32, 0x160f0
	v_writelane_b32 v242, s0, 20
	s_add_i32 s0, 32, 0x16130
	v_writelane_b32 v242, s0, 21
	s_add_i32 s0, 32, 0x16170
	v_writelane_b32 v242, s0, 22
	s_add_i32 s0, 32, 0x161b0
	v_writelane_b32 v242, s0, 23
	s_add_i32 s0, 32, 0x161f0
	v_writelane_b32 v242, s0, 24
	s_add_i32 s0, 32, 0x16010
	v_writelane_b32 v242, s0, 25
	s_add_i32 s0, 32, 0x16050
	v_writelane_b32 v242, s0, 26
	s_add_i32 s0, 32, 0x16090
	v_writelane_b32 v242, s0, 27
	s_add_i32 s0, 32, 0x160d0
	v_writelane_b32 v242, s0, 28
	s_add_i32 s0, 32, 0x16110
	v_writelane_b32 v242, s0, 29
	s_add_i32 s0, 32, 0x16150
	v_writelane_b32 v242, s0, 30
	s_add_i32 s0, 32, 0x16190
	v_writelane_b32 v242, s0, 31
	s_add_i32 s0, 32, 0x161d0
	v_writelane_b32 v242, s0, 32
	s_add_i32 s0, 32, 0x16040
	v_writelane_b32 v242, s0, 33
	s_add_i32 s0, 32, 0x16080
	v_writelane_b32 v242, s0, 34
	s_add_i32 s0, 32, 0x160c0
	v_writelane_b32 v242, s0, 35
	s_add_i32 s0, 32, 0x16100
	v_writelane_b32 v242, s0, 36
	s_add_i32 s0, 32, 0x16140
	v_writelane_b32 v242, s0, 37
	s_add_i32 s0, 32, 0x16180
	v_writelane_b32 v242, s0, 38
	s_add_i32 s0, 32, 0x161c0
	v_writelane_b32 v242, s0, 39
	s_mov_b32 s0, 0
	v_writelane_b32 v242, s0, 40
	s_lshl_b64 s[0:1], s[46:47], 13
	v_writelane_b32 v242, s0, 41
	s_movk_i32 s15, 0x7fff
	s_nop 0
	v_writelane_b32 v242, s1, 42
	v_writelane_b32 v242, s20, 43
	v_writelane_b32 v242, s21, 44
	v_writelane_b32 v242, s28, 45
	v_writelane_b32 v242, s29, 46
	s_mov_b64 s[0:1], -1
	v_writelane_b32 v242, s18, 47
	v_writelane_b32 v242, s19, 48
	s_branch .LBB0_431

.LBB0_794:
	s_and_b64 vcc, exec, s[38:39]
	s_cbranch_vccnz .LBB0_846
	v_readlane_b32 s6, v242, 0
	v_readlane_b32 s5, v242, 40
	v_readlane_b32 s7, v242, 1
	s_mul_i32 s2, s5, 0x180
	s_mov_b32 s3, s7
	s_lshl_b32 s4, s5, 3
	s_lshl_b64 s[2:3], s[2:3], 2
	s_add_u32 s30, s78, s2
	s_addc_u32 s31, s79, s3
	s_add_u32 s40, s82, s2
	s_addc_u32 s41, s83, s3
	s_mul_i32 s6, s5, 0x480
	s_add_u32 s42, s80, s2
	s_addc_u32 s43, s81, s3
	s_lshl_b64 s[2:3], s[6:7], 2
	s_add_u32 s94, s84, s2
	s_addc_u32 s95, s85, s3
	s_mov_b32 s2, 0xaaaaaaab
	v_mul_hi_u32 v255, v0, s2
	v_lshrrev_b32_e32 v255, 5, v255
	v_mul_u32_u24_e32 v241, 48, v255
	v_sub_u32_e32 v241, v0, v241
	v_lshlrev_b32_e32 v241, 4, v241
	v_lshl_add_u32 v241, v255, 12, v241
	v_cmp_gt_u32_e32 vcc, 62, v255
	v_cndmask_b32_e32 v234, -1, v255, vcc
	v_add_u32_e32 v254, 0x200, v0
	v_mul_hi_u32 v255, v254, s2
	v_lshrrev_b32_e32 v255, 5, v255
	v_mul_u32_u24_e32 v245, 48, v255
	v_sub_u32_e32 v245, v254, v245
	v_lshlrev_b32_e32 v245, 4, v245
	v_lshl_add_u32 v245, v255, 12, v245
	v_cmp_gt_u32_e32 vcc, 62, v255
	v_cndmask_b32_e32 v235, -1, v255, vcc
	v_add_u32_e32 v254, 0x400, v0
	v_mul_hi_u32 v255, v254, s2
	v_lshrrev_b32_e32 v255, 5, v255
	v_mul_u32_u24_e32 v246, 48, v255
	v_sub_u32_e32 v246, v254, v246
	v_lshlrev_b32_e32 v246, 4, v246
	v_lshl_add_u32 v246, v255, 12, v246
	v_cmp_gt_u32_e32 vcc, 62, v255
	v_cndmask_b32_e32 v236, -1, v255, vcc
	v_add_u32_e32 v254, 0x600, v0
	v_mul_hi_u32 v255, v254, s2
	v_lshrrev_b32_e32 v255, 5, v255
	v_mul_u32_u24_e32 v247, 48, v255
	v_sub_u32_e32 v247, v254, v247
	v_lshlrev_b32_e32 v247, 4, v247
	v_lshl_add_u32 v247, v255, 12, v247
	v_cmp_gt_u32_e32 vcc, 62, v255
	v_cndmask_b32_e32 v237, -1, v255, vcc
	v_add_u32_e32 v254, 0x800, v0
	v_mul_hi_u32 v255, v254, s2
	v_lshrrev_b32_e32 v255, 5, v255
	v_mul_u32_u24_e32 v252, 48, v255
	v_sub_u32_e32 v252, v254, v252
	v_lshlrev_b32_e32 v252, 4, v252
	v_lshl_add_u32 v252, v255, 12, v252
	v_cmp_gt_u32_e32 vcc, 62, v255
	v_cndmask_b32_e32 v238, -1, v255, vcc
	v_add_u32_e32 v254, 0xa00, v0
	v_mul_hi_u32 v255, v254, s2
	v_lshrrev_b32_e32 v255, 5, v255
	v_mul_u32_u24_e32 v253, 48, v255
	v_sub_u32_e32 v253, v254, v253
	v_lshlrev_b32_e32 v253, 4, v253
	v_lshl_add_u32 v253, v255, 12, v253
	v_cmp_gt_u32_e32 vcc, 62, v255
	v_cndmask_b32_e32 v239, -1, v255, vcc
	v_readlane_b32 s6, v242, 63
	v_and_b32_e32 v240, 63, v0
	v_min_u32_e32 v240, 47, v240
	v_lshlrev_b32_e32 v240, 5, v240
	global_load_dwordx4 v[186:189], v240, s[30:31]
	global_load_dwordx4 v[190:193], v240, s[30:31] offset:16
	global_load_dwordx4 v[194:197], v240, s[40:41]
	global_load_dwordx4 v[198:201], v240, s[40:41] offset:16
	global_load_dwordx4 v[202:205], v240, s[42:43]
	global_load_dwordx4 v[206:209], v240, s[42:43] offset:16
	global_load_dwordx4 v[210:213], v240, s[94:95] offset:3072
	global_load_dwordx4 v[214:217], v240, s[94:95] offset:3088
	global_load_dwordx4 v[218:221], v240, s[94:95] offset:1536
	global_load_dwordx4 v[222:225], v240, s[94:95] offset:1552
	global_load_dwordx4 v[226:229], v240, s[94:95]
	global_load_dwordx4 v[230:233], v240, s[94:95] offset:16
	s_branch .LBB0_797
